# latent attention: next tile's K/V loads issued one tile ahead into spare registers (tile description software-pipelined)
# speedup vs baseline: 1.0151x; 1.0086x over previous
.LBB0_581:
	s_mov_b32 s0, 0xf149f2ca
	s_nop 6
	v_max3_f32 v0, v64, s0, v65
	v_max3_f32 v0, v0, v66, v67
	v_max3_f32 v0, v0, v68, v69
	v_max3_f32 v0, v0, v70, v71
	v_max3_f32 v0, v0, v72, v73
	v_max3_f32 v0, v0, v74, v75
	v_max3_f32 v0, v0, v76, v77
	v_max3_f32 v0, v0, v78, v79
	v_max3_f32 v0, v0, v48, v49
	v_max3_f32 v0, v0, v50, v51
	v_max3_f32 v0, v0, v52, v53
	v_max3_f32 v0, v0, v54, v55
	v_and_b32_e32 v3, 64, v213
	v_max3_f32 v0, v0, v56, v57
	v_xor_b32_e32 v2, 32, v213
	v_add_u32_e32 v3, 64, v3
	v_max3_f32 v0, v0, v58, v59
	v_cmp_lt_i32_e32 vcc, v2, v3
	v_max3_f32 v0, v0, v60, v61
	v_max3_f32 v0, v0, v62, v63
	v_cndmask_b32_e32 v2, v213, v2, vcc
	v_lshlrev_b32_e32 v2, 2, v2
	ds_bpermute_b32 v2, v2, v0
	s_waitcnt lgkmcnt(0)
	v_max3_f32 v14, v151, v0, v2
	v_sub_f32_e32 v6, v68, v14
	v_mul_f32_e32 v6, 0x3fb8aa3b, v6
	v_exp_f32_e32 v15, v6
	v_sub_f32_e32 v6, v69, v14
	v_mul_f32_e32 v6, 0x3fb8aa3b, v6
	v_sub_f32_e32 v2, v64, v14
	v_exp_f32_e32 v64, v6
	v_sub_f32_e32 v6, v70, v14
	v_mul_f32_e32 v6, 0x3fb8aa3b, v6
	v_sub_f32_e32 v3, v65, v14
	v_exp_f32_e32 v65, v6
	v_sub_f32_e32 v6, v71, v14
	v_mul_f32_e32 v6, 0x3fb8aa3b, v6
	v_mul_f32_e32 v2, 0x3fb8aa3b, v2
	v_mul_f32_e32 v3, 0x3fb8aa3b, v3
	v_sub_f32_e32 v4, v66, v14
	v_exp_f32_e32 v66, v6
	v_sub_f32_e32 v6, v72, v14
	v_exp_f32_e32 v2, v2
	v_exp_f32_e32 v3, v3
	v_mul_f32_e32 v6, 0x3fb8aa3b, v6
	v_mul_f32_e32 v4, 0x3fb8aa3b, v4
	v_sub_f32_e32 v5, v67, v14
	v_exp_f32_e32 v67, v6
	v_sub_f32_e32 v6, v73, v14
	v_exp_f32_e32 v4, v4
	v_mul_f32_e32 v5, 0x3fb8aa3b, v5
	v_mul_f32_e32 v6, 0x3fb8aa3b, v6
	v_exp_f32_e32 v5, v5
	v_exp_f32_e32 v68, v6
	v_sub_f32_e32 v6, v74, v14
	v_mul_f32_e32 v6, 0x3fb8aa3b, v6
	v_cvt_pk_bf16_f32 v10, v2, v3
	v_add_f32_e32 v2, 0, v2
	v_exp_f32_e32 v69, v6
	v_sub_f32_e32 v6, v75, v14
	v_add_f32_e32 v2, v3, v2
	v_mul_f32_e32 v6, 0x3fb8aa3b, v6
	v_add_f32_e32 v2, v4, v2
	v_exp_f32_e32 v70, v6
	v_sub_f32_e32 v6, v76, v14
	v_add_f32_e32 v2, v5, v2
	v_mul_f32_e32 v6, 0x3fb8aa3b, v6
	v_add_f32_e32 v2, v15, v2
	v_exp_f32_e32 v71, v6
	v_sub_f32_e32 v6, v77, v14
	v_add_f32_e32 v2, v64, v2
	v_mul_f32_e32 v6, 0x3fb8aa3b, v6
	v_add_f32_e32 v2, v65, v2
	v_exp_f32_e32 v72, v6
	v_sub_f32_e32 v6, v78, v14
	v_add_f32_e32 v2, v66, v2
	v_mul_f32_e32 v6, 0x3fb8aa3b, v6
	v_add_f32_e32 v2, v67, v2
	v_exp_f32_e32 v73, v6
	v_sub_f32_e32 v6, v79, v14
	v_add_f32_e32 v2, v68, v2
	v_mul_f32_e32 v6, 0x3fb8aa3b, v6
	v_add_f32_e32 v2, v69, v2
	v_exp_f32_e32 v74, v6
	v_add_f32_e32 v2, v70, v2
	v_add_f32_e32 v2, v71, v2
	v_add_f32_e32 v2, v72, v2
	v_add_f32_e32 v2, v73, v2
	v_cvt_pk_bf16_f32 v12, v15, v64
	v_add_f32_e32 v64, v74, v2
	v_sub_f32_e32 v2, v48, v14
	v_mul_f32_e32 v2, 0x3fb8aa3b, v2
	v_cvt_pk_bf16_f32 v13, v65, v66
	v_exp_f32_e32 v65, v2
	v_sub_f32_e32 v2, v49, v14
	v_mul_f32_e32 v2, 0x3fb8aa3b, v2
	v_exp_f32_e32 v66, v2
	v_sub_f32_e32 v2, v50, v14
	v_mul_f32_e32 v2, 0x3fb8aa3b, v2
	v_cvt_pk_bf16_f32 v6, v67, v68
	v_exp_f32_e32 v67, v2
	v_sub_f32_e32 v2, v51, v14
	v_mul_f32_e32 v2, 0x3fb8aa3b, v2
	v_exp_f32_e32 v68, v2
	v_sub_f32_e32 v2, v52, v14
	v_mul_f32_e32 v2, 0x3fb8aa3b, v2
	v_exp_f32_e32 v52, v2
	v_sub_f32_e32 v2, v53, v14
	v_mul_f32_e32 v2, 0x3fb8aa3b, v2
	v_exp_f32_e32 v53, v2
	v_sub_f32_e32 v2, v54, v14
	v_mul_f32_e32 v2, 0x3fb8aa3b, v2
	v_exp_f32_e32 v54, v2
	v_sub_f32_e32 v2, v55, v14
	v_mul_f32_e32 v2, 0x3fb8aa3b, v2
	v_exp_f32_e32 v55, v2
	v_sub_f32_e32 v2, v56, v14
	v_mul_f32_e32 v2, 0x3fb8aa3b, v2
	v_exp_f32_e32 v56, v2
	v_sub_f32_e32 v2, v57, v14
	v_mul_f32_e32 v2, 0x3fb8aa3b, v2
	v_exp_f32_e32 v57, v2
	v_sub_f32_e32 v2, v58, v14
	v_mul_f32_e32 v2, 0x3fb8aa3b, v2
	v_exp_f32_e32 v58, v2
	v_sub_f32_e32 v2, v59, v14
	v_mul_f32_e32 v2, 0x3fb8aa3b, v2
	v_exp_f32_e32 v59, v2
	v_sub_f32_e32 v2, v60, v14
	v_mul_f32_e32 v2, 0x3fb8aa3b, v2
	v_exp_f32_e32 v60, v2
	v_sub_f32_e32 v2, v61, v14
	v_mul_f32_e32 v2, 0x3fb8aa3b, v2
	v_exp_f32_e32 v61, v2
	v_sub_f32_e32 v2, v62, v14
	v_mul_f32_e32 v2, 0x3fb8aa3b, v2
	v_exp_f32_e32 v62, v2
	v_sub_f32_e32 v2, v63, v14
	v_add_f32_e32 v63, v65, v64
	v_add_f32_e32 v63, v66, v63
	v_add_f32_e32 v63, v67, v63
	v_add_f32_e32 v63, v68, v63
	v_cvt_pk_bf16_f32 v50, v52, v53
	v_add_f32_e32 v52, v52, v63
	v_add_f32_e32 v52, v53, v52
	v_add_f32_e32 v52, v54, v52
	v_add_f32_e32 v52, v55, v52
	v_add_f32_e32 v52, v56, v52
	v_add_f32_e32 v52, v57, v52
	v_sub_f32_e32 v0, v151, v14
	v_add_f32_e32 v52, v58, v52
	v_mul_f32_e32 v0, 0x3fb8aa3b, v0
	v_add_f32_e32 v52, v59, v52
	v_mul_f32_e32 v2, 0x3fb8aa3b, v2
	v_add_f32_e32 v52, v60, v52
	v_exp_f32_e32 v0, v0
	v_add_u32_e32 v53, 0x2000, v150
	v_cvt_pk_bf16_f32 v11, v4, v5
	v_exp_f32_e32 v15, v2
	v_cvt_pk_bf16_f32 v51, v54, v55
	v_cvt_pk_bf16_f32 v2, v56, v57
	v_cvt_pk_bf16_f32 v3, v58, v59
	v_cvt_pk_bf16_f32 v4, v60, v61
	v_add_f32_e32 v52, v61, v52
	ds_read2_b64 v[54:57], v53 offset1:2
	ds_read2_b64 v[58:61], v53 offset0:4 offset1:6
	v_pk_mul_f32 v[46:47], v[46:47], v[0:1] op_sel_hi:[1,0]
	v_pk_mul_f32 v[44:45], v[44:45], v[0:1] op_sel_hi:[1,0]
	v_pk_mul_f32 v[42:43], v[42:43], v[0:1] op_sel_hi:[1,0]
	v_pk_mul_f32 v[40:41], v[40:41], v[0:1] op_sel_hi:[1,0]
	v_pk_mul_f32 v[38:39], v[38:39], v[0:1] op_sel_hi:[1,0]
	v_pk_mul_f32 v[36:37], v[36:37], v[0:1] op_sel_hi:[1,0]
	v_pk_mul_f32 v[34:35], v[34:35], v[0:1] op_sel_hi:[1,0]
	v_pk_mul_f32 v[32:33], v[32:33], v[0:1] op_sel_hi:[1,0]
	v_cvt_pk_bf16_f32 v7, v69, v70
	v_cvt_pk_bf16_f32 v8, v71, v72
	s_waitcnt lgkmcnt(1)
	v_mfma_f32_32x32x16_bf16 v[32:47], v[54:57], v[10:13], v[32:47]
	v_cvt_pk_bf16_f32 v9, v73, v74
	ds_read2_b64 v[54:57], v53 offset0:8 offset1:10
	v_cvt_pk_bf16_f32 v48, v65, v66
	v_cvt_pk_bf16_f32 v49, v67, v68
	v_cvt_pk_bf16_f32 v5, v62, v15
	v_pk_mul_f32 v[30:31], v[30:31], v[0:1] op_sel_hi:[1,0]
	v_pk_mul_f32 v[28:29], v[28:29], v[0:1] op_sel_hi:[1,0]
	s_waitcnt lgkmcnt(1)
	v_mfma_f32_32x32x16_bf16 v[32:47], v[58:61], v[6:9], v[32:47]
	v_mul_f32_e64 v26, v26, v0
	v_mul_f32_e64 v27, v27, v0
	v_mul_f32_e64 v24, v24, v0
	v_mul_f32_e64 v25, v25, v0
	v_mul_f32_e64 v22, v22, v0
	v_mul_f32_e64 v23, v23, v0
	v_pk_mul_f32 v[20:21], v[20:21], v[0:1] op_sel_hi:[1,0]
	v_pk_mul_f32 v[18:19], v[18:19], v[0:1] op_sel_hi:[1,0]
	v_pk_mul_f32 v[16:17], v[16:17], v[0:1] op_sel_hi:[1,0]
	v_add_f32_e32 v52, v62, v52
	s_waitcnt lgkmcnt(0)
	v_mfma_f32_32x32x16_bf16 v[32:47], v[54:57], v[48:51], v[32:47]
	ds_read2_b64 v[54:57], v53 offset0:12 offset1:14
	v_add_u32_e32 v53, 0x3000, v150
	v_mov_b32_e32 v151, v14
	s_waitcnt lgkmcnt(0)
	v_mfma_f32_32x32x16_bf16 v[32:47], v[54:57], v[2:5], v[32:47]
	ds_read2_b64 v[54:57], v53 offset0:32 offset1:34
	s_waitcnt lgkmcnt(0)
	v_mfma_f32_32x32x16_bf16 v[16:31], v[54:57], v[10:13], v[16:31]
	ds_read2_b64 v[10:13], v53 offset0:36 offset1:38
	s_waitcnt lgkmcnt(0)
	v_mfma_f32_32x32x16_bf16 v[16:31], v[10:13], v[6:9], v[16:31]
	ds_read2_b64 v[6:9], v53 offset0:40 offset1:42
	s_waitcnt lgkmcnt(0)
	v_mfma_f32_32x32x16_bf16 v[16:31], v[6:9], v[48:51], v[16:31]
	ds_read2_b64 v[6:9], v53 offset0:44 offset1:46
	s_waitcnt lgkmcnt(0)
	v_mfma_f32_32x32x16_bf16 v[16:31], v[6:9], v[2:5], v[16:31]
	v_add_f32_e32 v2, v15, v52
	v_fmac_f32_e32 v2, v105, v0
	v_mov_b32_e32 v105, v2
	s_cmp_lg_u32 s78, 0
	s_cbranch_scc1 .LBB0_576
	s_branch .Lat_cons

.LBB0_592:
	s_and_b64 vcc, exec, s[50:51]
	s_cbranch_vccz .LBB0_582
	v_lshl_add_u64 v[190:191], v[102:103], 2, s[0:1]
	v_lshlrev_b32_e32 v186, 2, v104
	v_mov_b32_e32 v187, v1
	s_add_u32 s46, s46, s57
	s_addc_u32 s47, s47, 0
	v_lshl_add_u64 v[184:185], v[190:191], 0, v[186:187]
	v_lshl_add_u64 v[188:189], v[102:103], 2, s[46:47]
	global_load_dwordx4 v[168:171], v[184:185], off offset:16
	global_load_dwordx4 v[172:175], v[184:185], off
	v_lshl_add_u64 v[188:189], v[188:189], 0, v[186:187]
	s_nop 0
	global_load_dwordx4 v[176:179], v[188:189], off
	global_load_dwordx4 v[180:183], v[188:189], off offset:16
.Lat_cons:
	v_mov_b32_e32 v10, v190
	v_mov_b32_e32 v11, v191
	v_lshlrev_b32_e32 v0, 2, v104
	s_barrier
	s_waitcnt vmcnt(0)
	v_mov_b32_e32 v2, v168
	v_mov_b32_e32 v3, v169
	v_mov_b32_e32 v4, v170
	v_mov_b32_e32 v5, v171
	v_mov_b32_e32 v6, v172
	v_mov_b32_e32 v7, v173
	v_mov_b32_e32 v8, v174
	v_mov_b32_e32 v9, v175
	v_cndmask_b32_e64 v12, 0, 1, s[48:49]
	v_cmp_ne_u32_e64 s[66:67], 1, v12
	s_mov_b32 s32, s74
	s_andn2_b64 vcc, exec, s[48:49]
	s_cbranch_vccnz .LBB0_595
	v_add_u32_e32 v12, s74, v100
	v_ashrrev_i32_e32 v13, 6, v12
	v_and_b32_e32 v12, 63, v12
	v_cndmask_b32_e64 v12, v12, v13, s[36:37]
	v_lshl_or_b32 v12, v12, 4, v109
	v_ashrrev_i32_e32 v13, 31, v12
	v_lshl_add_u64 v[56:57], v[12:13], 3, s[64:65]
	v_mov_b32_e32 v107, v1
	global_load_dwordx4 v[12:15], v[56:57], off
	global_load_dwordx4 v[48:51], v[56:57], off offset:16
	global_load_dwordx4 v[52:55], v[56:57], off offset:32
	s_nop 0
	global_load_dwordx4 v[56:59], v[56:57], off offset:48
	v_lshl_add_u64 v[10:11], v[10:11], 0, v[106:107]
	global_load_dwordx4 v[60:63], v[10:11], off
	global_load_dwordx4 v[64:67], v[10:11], off offset:16
	s_waitcnt vmcnt(5)
	v_mov_b32_e32 v10, v13
	v_mov_b32_e32 v11, v15
	v_mov_b32_e32 v13, v14
	s_waitcnt vmcnt(4)
	v_mov_b32_e32 v14, v49
	v_mov_b32_e32 v15, v51
	v_mov_b32_e32 v49, v50
	s_waitcnt vmcnt(3)
	v_mov_b32_e32 v50, v53
	v_mov_b32_e32 v51, v55
	v_mov_b32_e32 v53, v54
	s_waitcnt vmcnt(2)
	v_mov_b32_e32 v54, v57
	v_mov_b32_e32 v55, v59
	s_waitcnt vmcnt(1)
	v_pk_mul_f32 v[10:11], v[60:61], v[10:11]
	v_pk_mul_f32 v[14:15], v[62:63], v[14:15]
	s_waitcnt vmcnt(0)
	v_pk_mul_f32 v[50:51], v[64:65], v[50:51]
	v_pk_mul_f32 v[54:55], v[66:67], v[54:55]
	v_mov_b32_e32 v57, v58
	v_cndmask_b32_e64 v11, v11, -v11, s[38:39]
	v_cndmask_b32_e64 v10, v10, -v10, s[38:39]
	v_cndmask_b32_e64 v15, v15, -v15, s[38:39]
	v_cndmask_b32_e64 v14, v14, -v14, s[38:39]
	v_cndmask_b32_e64 v51, v51, -v51, s[38:39]
	v_cndmask_b32_e64 v50, v50, -v50, s[38:39]
	v_cndmask_b32_e64 v55, v55, -v55, s[38:39]
	v_cndmask_b32_e64 v54, v54, -v54, s[38:39]
	v_pk_fma_f32 v[6:7], v[6:7], v[12:13], v[10:11]
	v_pk_fma_f32 v[8:9], v[8:9], v[48:49], v[14:15]
	v_pk_fma_f32 v[2:3], v[2:3], v[52:53], v[50:51]
	v_pk_fma_f32 v[4:5], v[4:5], v[56:57], v[54:55]
.LBB0_595:
	v_cvt_pk_bf16_f32 v6, v6, v7
	v_cvt_pk_bf16_f32 v7, v8, v9
	v_cvt_pk_bf16_f32 v8, v2, v3
	v_cvt_pk_bf16_f32 v9, v4, v5
	ds_write_b128 v144, v[6:9]
	v_cvt_pk_bf16_f32 v0, v176, s0
	v_cvt_pk_bf16_f32 v2, v177, s0
	v_cvt_pk_bf16_f32 v3, v178, s0
	v_cvt_pk_bf16_f32 v4, v179, s0
	v_cvt_pk_bf16_f32 v5, v180, s0
	v_cvt_pk_bf16_f32 v6, v181, s0
	v_cvt_pk_bf16_f32 v7, v182, s0
	v_cvt_pk_bf16_f32 v8, v183, s0
	s_mov_b32 s78, 0
.Lat_adv:
	s_add_i32 s30, s30, 1
	s_addk_i32 s55, 0x2000
	s_add_i32 s56, s56, 64
	s_add_u32 s42, s42, 0x8000
	s_addc_u32 s43, s43, 0
	s_add_u32 s44, s44, 0x8000
	s_addc_u32 s45, s45, 0
	s_cmp_lg_u32 s29, s30
	s_cbranch_scc1 .Lat_desc
	s_mov_b32 s78, 1
	s_branch .Lat_go

.Lat_d592:
	s_and_b64 vcc, exec, s[50:51]
	s_and_b64 vcc, exec, s[50:51]
	s_cbranch_vccz .Lat_adv
	v_lshl_add_u64 v[190:191], v[102:103], 2, s[0:1]
	v_lshlrev_b32_e32 v186, 2, v104
	v_mov_b32_e32 v187, v1
	s_add_u32 s46, s46, s57
	s_addc_u32 s47, s47, 0
	v_lshl_add_u64 v[184:185], v[190:191], 0, v[186:187]
	v_lshl_add_u64 v[188:189], v[102:103], 2, s[46:47]
	global_load_dwordx4 v[168:171], v[184:185], off offset:16
	global_load_dwordx4 v[172:175], v[184:185], off
	v_lshl_add_u64 v[188:189], v[188:189], 0, v[186:187]
	s_nop 0
	global_load_dwordx4 v[176:179], v[188:189], off
	global_load_dwordx4 v[180:183], v[188:189], off offset:16
.Lat_go:
	ds_write_b16 v145, v0 offset:8192
	ds_write_b16 v145, v2 offset:8328
	ds_write_b16 v145, v3 offset:8464
	ds_write_b16 v145, v4 offset:8600
	ds_write_b16 v145, v5 offset:8736
	ds_write_b16 v145, v6 offset:8872
	ds_write_b16 v145, v7 offset:9008
	ds_write_b16 v145, v8 offset:9144
	s_and_b64 vcc, exec, s[66:67]
	s_waitcnt lgkmcnt(0)
	s_barrier
	ds_read_b128 v[2:5], v146
	s_waitcnt lgkmcnt(0)
	v_mfma_f32_32x32x16_bf16 v[64:79], v[2:5], v[80:83], 0
	ds_read_b128 v[2:5], v146 offset:4096
	s_waitcnt lgkmcnt(0)
	v_mfma_f32_32x32x16_bf16 v[48:63], v[2:5], v[80:83], 0
	ds_read_b128 v[2:5], v147
	s_waitcnt lgkmcnt(0)
	v_mfma_f32_32x32x16_bf16 v[64:79], v[2:5], v[84:87], v[64:79]
	ds_read_b128 v[2:5], v147 offset:4096
	s_waitcnt lgkmcnt(0)
	v_mfma_f32_32x32x16_bf16 v[48:63], v[2:5], v[84:87], v[48:63]
	ds_read_b128 v[2:5], v148
	s_waitcnt lgkmcnt(0)
	v_mfma_f32_32x32x16_bf16 v[64:79], v[2:5], v[88:91], v[64:79]
	ds_read_b128 v[2:5], v148 offset:4096
	s_waitcnt lgkmcnt(0)
	v_mfma_f32_32x32x16_bf16 v[48:63], v[2:5], v[88:91], v[48:63]
	ds_read_b128 v[2:5], v149
	s_waitcnt lgkmcnt(0)
	v_mfma_f32_32x32x16_bf16 v[64:79], v[2:5], v[92:95], v[64:79]
	ds_read_b128 v[2:5], v149 offset:4096
	s_waitcnt lgkmcnt(0)
	v_mfma_f32_32x32x16_bf16 v[48:63], v[2:5], v[92:95], v[48:63]
	s_cbranch_vccnz .LBB0_581
	v_add_u32_e32 v0, s32, v101
	v_sub_u32_e32 v2, v108, v0
	v_cmp_lt_u32_e32 vcc, s72, v2
	v_sub_u32_e32 v2, v0, v108
	s_movk_i32 s0, 0x101
	s_nop 2
	v_cndmask_b32_e32 v64, v216, v64, vcc
	v_cmp_gt_u32_e32 vcc, s0, v2
	v_sub_u32_e32 v2, v110, v0
	s_nop 0
	v_cndmask_b32_e32 v65, v216, v65, vcc
	v_cmp_lt_u32_e32 vcc, s72, v2
	v_sub_u32_e32 v2, v111, v0
	s_nop 0
	v_cndmask_b32_e32 v66, v216, v66, vcc
	v_cmp_lt_u32_e32 vcc, s72, v2
	v_sub_u32_e32 v2, v112, v0
	s_nop 0
	v_cndmask_b32_e32 v67, v216, v67, vcc
	v_cmp_lt_u32_e32 vcc, s72, v2
	v_sub_u32_e32 v2, v113, v0
	s_nop 0
	v_cndmask_b32_e32 v68, v216, v68, vcc
	v_cmp_lt_u32_e32 vcc, s72, v2
	v_sub_u32_e32 v2, v114, v0
	s_nop 0
	v_cndmask_b32_e32 v69, v216, v69, vcc
	v_cmp_lt_u32_e32 vcc, s72, v2
	v_sub_u32_e32 v2, v115, v0
	s_nop 0
	v_cndmask_b32_e32 v70, v216, v70, vcc
	v_cmp_lt_u32_e32 vcc, s72, v2
	v_sub_u32_e32 v2, v116, v0
	s_nop 0
	v_cndmask_b32_e32 v71, v216, v71, vcc
	v_cmp_lt_u32_e32 vcc, s72, v2
	v_sub_u32_e32 v2, v117, v0
	s_nop 0
	v_cndmask_b32_e32 v72, v216, v72, vcc
	v_cmp_lt_u32_e32 vcc, s72, v2
	v_sub_u32_e32 v2, v118, v0
	s_nop 0
	v_cndmask_b32_e32 v73, v216, v73, vcc
	v_cmp_lt_u32_e32 vcc, s72, v2
	v_sub_u32_e32 v2, v119, v0
	s_nop 0
	v_cndmask_b32_e32 v74, v216, v74, vcc
	v_cmp_lt_u32_e32 vcc, s72, v2
	v_sub_u32_e32 v2, v120, v0
	s_nop 0
	v_cndmask_b32_e32 v75, v216, v75, vcc
	v_cmp_lt_u32_e32 vcc, s72, v2
	v_sub_u32_e32 v2, v121, v0
	s_nop 0
	v_cndmask_b32_e32 v76, v216, v76, vcc
	v_cmp_lt_u32_e32 vcc, s72, v2
	v_sub_u32_e32 v2, v122, v0
	s_nop 0
	v_cndmask_b32_e32 v77, v216, v77, vcc
	v_cmp_lt_u32_e32 vcc, s72, v2
	v_sub_u32_e32 v2, v123, v0
	s_nop 0
	v_cndmask_b32_e32 v78, v216, v78, vcc
	v_cmp_lt_u32_e32 vcc, s72, v2
	v_sub_u32_e32 v2, v124, v0
	s_nop 0
	v_cndmask_b32_e32 v79, v216, v79, vcc
	v_cmp_lt_u32_e32 vcc, s72, v2
	v_sub_u32_e32 v2, v125, v0
	s_nop 0
	v_cndmask_b32_e32 v48, v216, v48, vcc
	v_cmp_lt_u32_e32 vcc, s72, v2
	v_sub_u32_e32 v2, v126, v0
	s_nop 0
	v_cndmask_b32_e32 v49, v216, v49, vcc
	v_cmp_lt_u32_e32 vcc, s72, v2
	v_sub_u32_e32 v2, v127, v0
	s_nop 0
	v_cndmask_b32_e32 v50, v216, v50, vcc
	v_cmp_lt_u32_e32 vcc, s72, v2
	v_sub_u32_e32 v2, v128, v0
	s_nop 0
	v_cndmask_b32_e32 v51, v216, v51, vcc
	v_cmp_lt_u32_e32 vcc, s72, v2
	v_sub_u32_e32 v2, v129, v0
	s_nop 0
	v_cndmask_b32_e32 v52, v216, v52, vcc
	v_cmp_lt_u32_e32 vcc, s72, v2
	v_sub_u32_e32 v2, v130, v0
	s_nop 0
	v_cndmask_b32_e32 v53, v216, v53, vcc
	v_cmp_lt_u32_e32 vcc, s72, v2
	v_sub_u32_e32 v2, v131, v0
	s_nop 0
	v_cndmask_b32_e32 v54, v216, v54, vcc
	v_cmp_lt_u32_e32 vcc, s72, v2
	v_sub_u32_e32 v2, v132, v0
	s_nop 0
	v_cndmask_b32_e32 v55, v216, v55, vcc
	v_cmp_lt_u32_e32 vcc, s72, v2
	v_sub_u32_e32 v2, v133, v0
	s_nop 0
	v_cndmask_b32_e32 v56, v216, v56, vcc
	v_cmp_lt_u32_e32 vcc, s72, v2
	v_sub_u32_e32 v2, v138, v0
	s_nop 0
	v_cndmask_b32_e32 v57, v216, v57, vcc
	v_cmp_lt_u32_e32 vcc, s72, v2
	v_sub_u32_e32 v2, v139, v0
	s_nop 0
	v_cndmask_b32_e32 v58, v216, v58, vcc
	v_cmp_lt_u32_e32 vcc, s72, v2
	v_sub_u32_e32 v2, v140, v0
	s_nop 0
	v_cndmask_b32_e32 v59, v216, v59, vcc
	v_cmp_lt_u32_e32 vcc, s72, v2
	v_sub_u32_e32 v2, v141, v0
	s_nop 0
	v_cndmask_b32_e32 v60, v216, v60, vcc
	v_cmp_lt_u32_e32 vcc, s72, v2
	v_sub_u32_e32 v2, v142, v0
	v_sub_u32_e32 v0, v143, v0
	v_cndmask_b32_e32 v61, v216, v61, vcc
	v_cmp_lt_u32_e32 vcc, s72, v2
	s_nop 1
	v_cndmask_b32_e32 v62, v216, v62, vcc
	v_cmp_lt_u32_e32 vcc, s72, v0
	s_nop 1
	v_cndmask_b32_e32 v63, v216, v63, vcc
	s_branch .LBB0_581
